# up-GEMM loop: the leading wave half waits for its LDS-DMA pieces at the end of its following MMA section (one interval later) instead of inside its load section
# baseline (speedup 1.0000x reference)
; #define PG8_STAGE(bufoff, gbase, voff) do { _Pragma("unroll") for (int _i = 0; _i < 2; ++_i) \
;         __builtin_amdgcn_global_load_lds((const unsigned*)((const char*)(gbase) + (voff)[_i]), (LAS unsigned*)(lds + (bufoff) + ldsw + _i * 8192), 16, 0, 0); } while (0)
; #define PG8_LDA(dst, b, h) do { _Pragma("unroll") for (int m = 0; m < NM; ++m) _Pragma("unroll") for (int k = 0; k < 2; ++k) dst[m][k] = *(const LAS bf16x8*)(lds + PG8_SA(b, h) + aoff + m * 2048 + k * 1024); } while (0)
; #define PG8_LDB(dst, b, h) do { _Pragma("unroll") for (int n = 0; n < 2; ++n) _Pragma("unroll") for (int k = 0; k < 2; ++k) dst[n][k] = *(const LAS bf16x8*)(lds + PG8_SB(b, h) + boff + n * 2048 + k * 1024); } while (0)
; #define PG8_MMA(ai, bj, At, Bt) do { __builtin_amdgcn_s_setprio(1); _Pragma("unroll") for (int m = 0; m < NM; ++m) _Pragma("unroll") for (int n = 0; n < 2; ++n) _Pragma("unroll") for (int k = 0; k < 2; ++k) \
;         acc[ai][bj][m][n] = __builtin_amdgcn_mfma_f32_16x16x32_bf16(Bt[n][k], At[m][k], acc[ai][bj][m][n], 0, 0, 0); __builtin_amdgcn_s_setprio(0); } while (0)
; #define PG8_WAIT_V(n) asm volatile("s_waitcnt vmcnt(" #n ")" ::: "memory")
; #define PG8_WAIT_L(n) asm volatile("s_waitcnt lgkmcnt(" #n ")" ::: "memory")
; #define PG8_BAR __builtin_amdgcn_s_barrier()
; #define PG8_SCHED __builtin_amdgcn_sched_barrier(0)
;     ...
;             PG8_LDB(B0, 0, 0); PG8_LDB(B1, 0, 1); PG8_SCHED; PG8_LDA(At, 0, 0); PG8_STAGE(PG8_SA(1, 1), a1 + hstepA, voffA);
;             PG8_WAIT_V(8); PG8_WAIT_L(0); PG8_BAR; PG8_MMA(0, 0, At, B0); PG8_MMA(0, 1, At, B1); PG8_BAR; PG8_SCHED;
;             PG8_LDA(At, 0, 1); PG8_STAGE(PG8_SB(0, 0), b2, voffB); PG8_STAGE(PG8_SB(0, 1), b2 + hstepB, voffB); PG8_STAGE(PG8_SA(0, 0), a2, voffA);
;             PG8_WAIT_V(8); PG8_WAIT_L(0); PG8_BAR; PG8_MMA(1, 0, At, B0); PG8_MMA(1, 1, At, B1); PG8_BAR; PG8_SCHED;
.LBB0_1783:
	v_add_u32_e32 v0, s64, v208
	ds_read_b128 v[130:133], v0
	ds_read_b128 v[134:137], v0 offset:1024
	ds_read_b128 v[138:141], v0 offset:2048
	ds_read_b128 v[142:145], v0 offset:3072
	v_add_u32_e32 v0, s70, v208
	ds_read_b128 v[146:149], v0
	ds_read_b128 v[150:153], v0 offset:1024
	ds_read_b128 v[154:157], v0 offset:2048
	ds_read_b128 v[158:161], v0 offset:3072
	s_add_u32 s14, s12, 0xfff80080
	s_addc_u32 s15, s13, -1
	s_cmp_eq_u32 vcc_lo, 28
	s_cselect_b32 s47, s2, s15
	s_cselect_b32 s46, s3, s14
	s_cselect_b32 s15, s9, s41
	s_cselect_b32 s14, s11, s37
	s_cselect_b32 s100, -1, 0
	s_andn2_b32 s100, s100, s101
	s_add_i32 m0, s73, 0xc000
	ds_read_b128 v[162:165], v209
	ds_read_b128 v[166:169], v209 offset:1024
	ds_read_b128 v[170:173], v209 offset:2048
	ds_read_b128 v[174:177], v209 offset:3072
	ds_read_b128 v[190:193], v209 offset:4096
	ds_read_b128 v[194:197], v209 offset:5120
	ds_read_b128 v[198:201], v209 offset:6144
	ds_read_b128 v[202:205], v209 offset:7168
	global_load_lds_dwordx4 v186, s[12:13]
	s_add_i32 m0, s73, 0xe000
	s_nop 0
	global_load_lds_dwordx4 v188, s[12:13]
	s_cmp_eq_u64 s[24:25], 0
	s_cbranch_scc0 .Lmw_up0
	s_waitcnt vmcnt(8)
.Lmw_up0:
	s_waitcnt lgkmcnt(0)
	s_barrier
	s_setprio 1
	s_waitcnt lgkmcnt(0)
	v_mfma_f32_16x16x32_bf16 v[126:129], v[130:133], v[162:165], v[126:129]
	v_mfma_f32_16x16x32_bf16 v[94:97], v[138:141], v[162:165], v[94:97]
	v_mfma_f32_16x16x32_bf16 v[110:113], v[130:133], v[170:173], v[110:113]
	v_mfma_f32_16x16x32_bf16 v[70:73], v[138:141], v[170:173], v[70:73]
	v_mfma_f32_16x16x32_bf16 v[106:109], v[130:133], v[190:193], v[106:109]
	v_mfma_f32_16x16x32_bf16 v[66:69], v[138:141], v[190:193], v[66:69]
	v_mfma_f32_16x16x32_bf16 v[118:121], v[130:133], v[198:201], v[118:121]
	v_mfma_f32_16x16x32_bf16 v[86:89], v[138:141], v[198:201], v[86:89]
	v_mfma_f32_16x16x32_bf16 v[126:129], v[134:137], v[166:169], v[126:129]
	v_mfma_f32_16x16x32_bf16 v[94:97], v[142:145], v[166:169], v[94:97]
	v_mfma_f32_16x16x32_bf16 v[110:113], v[134:137], v[174:177], v[110:113]
	v_mfma_f32_16x16x32_bf16 v[70:73], v[142:145], v[174:177], v[70:73]
	v_mfma_f32_16x16x32_bf16 v[106:109], v[134:137], v[194:197], v[106:109]
	v_mfma_f32_16x16x32_bf16 v[66:69], v[142:145], v[194:197], v[66:69]
	v_mfma_f32_16x16x32_bf16 v[118:121], v[134:137], v[202:205], v[118:121]
	v_mfma_f32_16x16x32_bf16 v[86:89], v[142:145], v[202:205], v[86:89]
	s_setprio 0
	s_setprio 1
	v_mfma_f32_16x16x32_bf16 v[122:125], v[146:149], v[162:165], v[122:125]
	v_mfma_f32_16x16x32_bf16 v[90:93], v[154:157], v[162:165], v[90:93]
	v_mfma_f32_16x16x32_bf16 v[102:105], v[146:149], v[170:173], v[102:105]
	v_mfma_f32_16x16x32_bf16 v[62:65], v[154:157], v[170:173], v[62:65]
	v_mfma_f32_16x16x32_bf16 v[98:101], v[146:149], v[190:193], v[98:101]
	v_mfma_f32_16x16x32_bf16 v[58:61], v[154:157], v[190:193], v[58:61]
	v_mfma_f32_16x16x32_bf16 v[114:117], v[146:149], v[198:201], v[114:117]
	v_mfma_f32_16x16x32_bf16 v[82:85], v[154:157], v[198:201], v[82:85]
	v_mfma_f32_16x16x32_bf16 v[122:125], v[150:153], v[166:169], v[122:125]
	v_mfma_f32_16x16x32_bf16 v[90:93], v[158:161], v[166:169], v[90:93]
	v_mfma_f32_16x16x32_bf16 v[102:105], v[150:153], v[174:177], v[102:105]
	v_mfma_f32_16x16x32_bf16 v[62:65], v[158:161], v[174:177], v[62:65]
	v_mfma_f32_16x16x32_bf16 v[98:101], v[150:153], v[194:197], v[98:101]
	v_mfma_f32_16x16x32_bf16 v[58:61], v[158:161], v[194:197], v[58:61]
	v_mfma_f32_16x16x32_bf16 v[114:117], v[150:153], v[202:205], v[114:117]
	v_mfma_f32_16x16x32_bf16 v[82:85], v[158:161], v[202:205], v[82:85]
	s_setprio 0
	s_waitcnt vmcnt(8)
	s_barrier
	s_mov_b32 m0, s68
	s_add_u32 s22, s14, 0x80000
	s_addc_u32 s23, s15, 0
	ds_read_b128 v[162:165], v209 offset:16384
	ds_read_b128 v[166:169], v209 offset:17408
	ds_read_b128 v[170:173], v209 offset:18432
	ds_read_b128 v[174:177], v209 offset:19456
	ds_read_b128 v[190:193], v209 offset:20480
	ds_read_b128 v[194:197], v209 offset:21504
	ds_read_b128 v[198:201], v209 offset:22528
	ds_read_b128 v[202:205], v209 offset:23552
	s_cmp_lg_u32 s100, 0
	s_cbranch_scc1 .Ltl_up_0s
	global_load_lds_dwordx4 v180, s[14:15]
	s_mov_b32 m0, s69
	s_nop 0
	global_load_lds_dwordx4 v184, s[14:15]
	s_mov_b32 m0, s71
	s_nop 0
	global_load_lds_dwordx4 v180, s[22:23]
	s_mov_b32 m0, s72
	s_nop 0
	global_load_lds_dwordx4 v184, s[22:23]
	s_mov_b32 m0, s73
	s_nop 0
	global_load_lds_dwordx4 v178, s[46:47]
	s_mov_b32 m0, s74
	s_nop 0
	global_load_lds_dwordx4 v182, s[46:47]
	s_cmp_eq_u64 s[24:25], 0
	s_cbranch_scc0 .Lmw_up1
	s_waitcnt vmcnt(8)

; #define PG8_STAGE(bufoff, gbase, voff) do { _Pragma("unroll") for (int _i = 0; _i < 2; ++_i) \
;         __builtin_amdgcn_global_load_lds((const unsigned*)((const char*)(gbase) + (voff)[_i]), (LAS unsigned*)(lds + (bufoff) + ldsw + _i * 8192), 16, 0, 0); } while (0)
; #define PG8_LDA(dst, b, h) do { _Pragma("unroll") for (int m = 0; m < NM; ++m) _Pragma("unroll") for (int k = 0; k < 2; ++k) dst[m][k] = *(const LAS bf16x8*)(lds + PG8_SA(b, h) + aoff + m * 2048 + k * 1024); } while (0)
; #define PG8_LDB(dst, b, h) do { _Pragma("unroll") for (int n = 0; n < 2; ++n) _Pragma("unroll") for (int k = 0; k < 2; ++k) dst[n][k] = *(const LAS bf16x8*)(lds + PG8_SB(b, h) + boff + n * 2048 + k * 1024); } while (0)
; #define PG8_MMA(ai, bj, At, Bt) do { __builtin_amdgcn_s_setprio(1); _Pragma("unroll") for (int m = 0; m < NM; ++m) _Pragma("unroll") for (int n = 0; n < 2; ++n) _Pragma("unroll") for (int k = 0; k < 2; ++k) \
;         acc[ai][bj][m][n] = __builtin_amdgcn_mfma_f32_16x16x32_bf16(Bt[n][k], At[m][k], acc[ai][bj][m][n], 0, 0, 0); __builtin_amdgcn_s_setprio(0); } while (0)
; #define PG8_WAIT_V(n) asm volatile("s_waitcnt vmcnt(" #n ")" ::: "memory")
; #define PG8_WAIT_L(n) asm volatile("s_waitcnt lgkmcnt(" #n ")" ::: "memory")
; #define PG8_BAR __builtin_amdgcn_s_barrier()
; #define PG8_SCHED __builtin_amdgcn_sched_barrier(0)
;     ...
;             PG8_WAIT_V(8); PG8_WAIT_L(0); PG8_BAR; PG8_MMA(1, 0, At, B0); PG8_MMA(1, 1, At, B1); PG8_BAR; PG8_SCHED;
;             PG8_LDB(B0, 1, 0); PG8_LDB(B1, 1, 1); PG8_SCHED; PG8_LDA(At, 1, 0); PG8_STAGE(PG8_SA(0, 1), a2 + hstepA, voffA);
;             PG8_WAIT_V(8); PG8_WAIT_L(0); PG8_BAR; PG8_MMA(0, 0, At, B0); PG8_MMA(0, 1, At, B1); PG8_BAR; PG8_SCHED;
.Ltl_up_0d:
	s_waitcnt lgkmcnt(0)
	s_barrier
	s_setprio 1
	s_waitcnt lgkmcnt(0)
	v_mfma_f32_16x16x32_bf16 v[46:49], v[130:133], v[162:165], v[46:49]
	v_mfma_f32_16x16x32_bf16 v[22:25], v[138:141], v[162:165], v[22:25]
	v_mfma_f32_16x16x32_bf16 v[42:45], v[130:133], v[170:173], v[42:45]
	v_mfma_f32_16x16x32_bf16 v[18:21], v[138:141], v[170:173], v[18:21]
	v_mfma_f32_16x16x32_bf16 v[38:41], v[130:133], v[190:193], v[38:41]
	v_mfma_f32_16x16x32_bf16 v[14:17], v[138:141], v[190:193], v[14:17]
	v_mfma_f32_16x16x32_bf16 v[78:81], v[130:133], v[198:201], v[78:81]
	v_mfma_f32_16x16x32_bf16 v[54:57], v[138:141], v[198:201], v[54:57]
	v_mfma_f32_16x16x32_bf16 v[46:49], v[134:137], v[166:169], v[46:49]
	v_mfma_f32_16x16x32_bf16 v[22:25], v[142:145], v[166:169], v[22:25]
	v_mfma_f32_16x16x32_bf16 v[42:45], v[134:137], v[174:177], v[42:45]
	v_mfma_f32_16x16x32_bf16 v[18:21], v[142:145], v[174:177], v[18:21]
	v_mfma_f32_16x16x32_bf16 v[38:41], v[134:137], v[194:197], v[38:41]
	v_mfma_f32_16x16x32_bf16 v[14:17], v[142:145], v[194:197], v[14:17]
	v_mfma_f32_16x16x32_bf16 v[78:81], v[134:137], v[202:205], v[78:81]
	v_mfma_f32_16x16x32_bf16 v[54:57], v[142:145], v[202:205], v[54:57]
	s_setprio 0
	s_setprio 1
	v_mfma_f32_16x16x32_bf16 v[34:37], v[146:149], v[162:165], v[34:37]
	v_mfma_f32_16x16x32_bf16 v[10:13], v[154:157], v[162:165], v[10:13]
	v_mfma_f32_16x16x32_bf16 v[30:33], v[146:149], v[170:173], v[30:33]
	v_mfma_f32_16x16x32_bf16 v[6:9], v[154:157], v[170:173], v[6:9]
	v_mfma_f32_16x16x32_bf16 v[26:29], v[146:149], v[190:193], v[26:29]
	v_mfma_f32_16x16x32_bf16 v[2:5], v[154:157], v[190:193], v[2:5]
	v_mfma_f32_16x16x32_bf16 v[74:77], v[146:149], v[198:201], v[74:77]
	v_mfma_f32_16x16x32_bf16 v[50:53], v[154:157], v[198:201], v[50:53]
	v_mfma_f32_16x16x32_bf16 v[34:37], v[150:153], v[166:169], v[34:37]
	v_mfma_f32_16x16x32_bf16 v[10:13], v[158:161], v[166:169], v[10:13]
	v_mfma_f32_16x16x32_bf16 v[30:33], v[150:153], v[174:177], v[30:33]
	v_mfma_f32_16x16x32_bf16 v[6:9], v[158:161], v[174:177], v[6:9]
	v_mfma_f32_16x16x32_bf16 v[26:29], v[150:153], v[194:197], v[26:29]
	v_mfma_f32_16x16x32_bf16 v[2:5], v[158:161], v[194:197], v[2:5]
	v_mfma_f32_16x16x32_bf16 v[74:77], v[150:153], v[202:205], v[74:77]
	v_mfma_f32_16x16x32_bf16 v[50:53], v[158:161], v[202:205], v[50:53]
	s_setprio 0
	s_waitcnt vmcnt(8)
	s_barrier
	v_add_u32_e32 v0, s94, v208
	ds_read_b128 v[130:133], v0
	ds_read_b128 v[134:137], v0 offset:1024
	ds_read_b128 v[138:141], v0 offset:2048
	ds_read_b128 v[142:145], v0 offset:3072
	v_add_u32_e32 v0, s62, v208
	ds_read_b128 v[146:149], v0
	ds_read_b128 v[150:153], v0 offset:1024
	ds_read_b128 v[154:157], v0 offset:2048
	ds_read_b128 v[158:161], v0 offset:3072
	s_add_u32 s22, s46, 0x80000
	s_addc_u32 s23, s47, 0
	s_mov_b32 m0, s75
	ds_read_b128 v[162:165], v209 offset:32768
	ds_read_b128 v[166:169], v209 offset:33792
	ds_read_b128 v[170:173], v209 offset:34816
	ds_read_b128 v[174:177], v209 offset:35840
	ds_read_b128 v[190:193], v209 offset:36864
	ds_read_b128 v[194:197], v209 offset:37888
	ds_read_b128 v[198:201], v209 offset:38912
	ds_read_b128 v[202:205], v209 offset:39936
	s_cmp_lg_u32 s100, 0
	s_cbranch_scc1 .Ltl_up_1s
	global_load_lds_dwordx4 v178, s[22:23]
	s_mov_b32 m0, s80
	s_nop 0
	global_load_lds_dwordx4 v182, s[22:23]
	s_cmp_eq_u64 s[24:25], 0
	s_cbranch_scc0 .Lmw_up2
	s_waitcnt vmcnt(8)

; #define PG8_STAGE(bufoff, gbase, voff) do { _Pragma("unroll") for (int _i = 0; _i < 2; ++_i) \
;         __builtin_amdgcn_global_load_lds((const unsigned*)((const char*)(gbase) + (voff)[_i]), (LAS unsigned*)(lds + (bufoff) + ldsw + _i * 8192), 16, 0, 0); } while (0)
; #define PG8_LDA(dst, b, h) do { _Pragma("unroll") for (int m = 0; m < NM; ++m) _Pragma("unroll") for (int k = 0; k < 2; ++k) dst[m][k] = *(const LAS bf16x8*)(lds + PG8_SA(b, h) + aoff + m * 2048 + k * 1024); } while (0)
; #define PG8_MMA(ai, bj, At, Bt) do { __builtin_amdgcn_s_setprio(1); _Pragma("unroll") for (int m = 0; m < NM; ++m) _Pragma("unroll") for (int n = 0; n < 2; ++n) _Pragma("unroll") for (int k = 0; k < 2; ++k) \
;         acc[ai][bj][m][n] = __builtin_amdgcn_mfma_f32_16x16x32_bf16(Bt[n][k], At[m][k], acc[ai][bj][m][n], 0, 0, 0); __builtin_amdgcn_s_setprio(0); } while (0)
; #define PG8_WAIT_V(n) asm volatile("s_waitcnt vmcnt(" #n ")" ::: "memory")
; #define PG8_WAIT_L(n) asm volatile("s_waitcnt lgkmcnt(" #n ")" ::: "memory")
; #define PG8_BAR __builtin_amdgcn_s_barrier()
; #define PG8_SCHED __builtin_amdgcn_sched_barrier(0)
;     ...
;             PG8_WAIT_V(8); PG8_WAIT_L(0); PG8_BAR; PG8_MMA(0, 0, At, B0); PG8_MMA(0, 1, At, B1); PG8_BAR; PG8_SCHED;
;             PG8_LDA(At, 1, 1); PG8_STAGE(PG8_SB(1, 0), b3, voffB); PG8_STAGE(PG8_SB(1, 1), b3 + hstepB, voffB); PG8_STAGE(PG8_SA(1, 0), a3, voffA);
;             PG8_WAIT_V(8); PG8_WAIT_L(0); PG8_BAR; PG8_MMA(1, 0, At, B0); PG8_MMA(1, 1, At, B1); PG8_BAR; PG8_SCHED;
.Ltl_up_1d:
	s_waitcnt lgkmcnt(0)
	s_barrier
	s_setprio 1
	s_waitcnt lgkmcnt(0)
	v_mfma_f32_16x16x32_bf16 v[126:129], v[130:133], v[162:165], v[126:129]
	v_mfma_f32_16x16x32_bf16 v[94:97], v[138:141], v[162:165], v[94:97]
	v_mfma_f32_16x16x32_bf16 v[110:113], v[130:133], v[170:173], v[110:113]
	v_mfma_f32_16x16x32_bf16 v[70:73], v[138:141], v[170:173], v[70:73]
	v_mfma_f32_16x16x32_bf16 v[106:109], v[130:133], v[190:193], v[106:109]
	v_mfma_f32_16x16x32_bf16 v[66:69], v[138:141], v[190:193], v[66:69]
	v_mfma_f32_16x16x32_bf16 v[118:121], v[130:133], v[198:201], v[118:121]
	v_mfma_f32_16x16x32_bf16 v[86:89], v[138:141], v[198:201], v[86:89]
	v_mfma_f32_16x16x32_bf16 v[126:129], v[134:137], v[166:169], v[126:129]
	v_mfma_f32_16x16x32_bf16 v[94:97], v[142:145], v[166:169], v[94:97]
	v_mfma_f32_16x16x32_bf16 v[110:113], v[134:137], v[174:177], v[110:113]
	v_mfma_f32_16x16x32_bf16 v[70:73], v[142:145], v[174:177], v[70:73]
	v_mfma_f32_16x16x32_bf16 v[106:109], v[134:137], v[194:197], v[106:109]
	v_mfma_f32_16x16x32_bf16 v[66:69], v[142:145], v[194:197], v[66:69]
	v_mfma_f32_16x16x32_bf16 v[118:121], v[134:137], v[202:205], v[118:121]
	v_mfma_f32_16x16x32_bf16 v[86:89], v[142:145], v[202:205], v[86:89]
	s_setprio 0
	s_setprio 1
	v_mfma_f32_16x16x32_bf16 v[122:125], v[146:149], v[162:165], v[122:125]
	v_mfma_f32_16x16x32_bf16 v[90:93], v[154:157], v[162:165], v[90:93]
	v_mfma_f32_16x16x32_bf16 v[102:105], v[146:149], v[170:173], v[102:105]
	v_mfma_f32_16x16x32_bf16 v[62:65], v[154:157], v[170:173], v[62:65]
	v_mfma_f32_16x16x32_bf16 v[98:101], v[146:149], v[190:193], v[98:101]
	v_mfma_f32_16x16x32_bf16 v[58:61], v[154:157], v[190:193], v[58:61]
	v_mfma_f32_16x16x32_bf16 v[114:117], v[146:149], v[198:201], v[114:117]
	v_mfma_f32_16x16x32_bf16 v[82:85], v[154:157], v[198:201], v[82:85]
	v_mfma_f32_16x16x32_bf16 v[122:125], v[150:153], v[166:169], v[122:125]
	v_mfma_f32_16x16x32_bf16 v[90:93], v[158:161], v[166:169], v[90:93]
	v_mfma_f32_16x16x32_bf16 v[102:105], v[150:153], v[174:177], v[102:105]
	v_mfma_f32_16x16x32_bf16 v[62:65], v[158:161], v[174:177], v[62:65]
	v_mfma_f32_16x16x32_bf16 v[98:101], v[150:153], v[194:197], v[98:101]
	v_mfma_f32_16x16x32_bf16 v[58:61], v[158:161], v[194:197], v[58:61]
	v_mfma_f32_16x16x32_bf16 v[114:117], v[150:153], v[202:205], v[114:117]
	v_mfma_f32_16x16x32_bf16 v[82:85], v[158:161], v[202:205], v[82:85]
	s_setprio 0
	s_waitcnt vmcnt(8)
	s_barrier
	s_mov_b32 m0, s51
	s_add_u32 s22, s14, s66
	s_addc_u32 s23, s15, s67
	s_add_u32 s14, s14, 0x80080
	s_addc_u32 s15, s15, 0
	ds_read_b128 v[162:165], v209 offset:49152
	ds_read_b128 v[166:169], v209 offset:50176
	ds_read_b128 v[170:173], v209 offset:51200
	ds_read_b128 v[174:177], v209 offset:52224
	ds_read_b128 v[190:193], v209 offset:53248
	ds_read_b128 v[194:197], v209 offset:54272
	ds_read_b128 v[198:201], v209 offset:55296
	ds_read_b128 v[202:205], v209 offset:56320
	s_cmp_lg_u32 s100, 0
	s_cbranch_scc1 .Ltl_up_2s
	global_load_lds_dwordx4 v180, s[22:23]
	s_mov_b32 m0, s95
	s_nop 0
	global_load_lds_dwordx4 v184, s[22:23]
	s_add_u32 s22, s46, s66
	s_addc_u32 s23, s47, s67
	s_mov_b32 m0, s50
	s_nop 0
	global_load_lds_dwordx4 v180, s[14:15]
	s_mov_b32 m0, s49
	s_nop 0
	global_load_lds_dwordx4 v184, s[14:15]
	s_mov_b32 m0, s58
	s_nop 0
	global_load_lds_dwordx4 v178, s[22:23]
	s_mov_b32 m0, s59
	s_nop 0
	global_load_lds_dwordx4 v182, s[22:23]
	s_cmp_eq_u64 s[24:25], 0
	s_cbranch_scc0 .Lmw_up3
	s_waitcnt vmcnt(8)

; #define PG8_STAGE(bufoff, gbase, voff) do { _Pragma("unroll") for (int _i = 0; _i < 2; ++_i) \
;         __builtin_amdgcn_global_load_lds((const unsigned*)((const char*)(gbase) + (voff)[_i]), (LAS unsigned*)(lds + (bufoff) + ldsw + _i * 8192), 16, 0, 0); } while (0)
; #define PG8_LDA(dst, b, h) do { _Pragma("unroll") for (int m = 0; m < NM; ++m) _Pragma("unroll") for (int k = 0; k < 2; ++k) dst[m][k] = *(const LAS bf16x8*)(lds + PG8_SA(b, h) + aoff + m * 2048 + k * 1024); } while (0)
; #define PG8_LDB(dst, b, h) do { _Pragma("unroll") for (int n = 0; n < 2; ++n) _Pragma("unroll") for (int k = 0; k < 2; ++k) dst[n][k] = *(const LAS bf16x8*)(lds + PG8_SB(b, h) + boff + n * 2048 + k * 1024); } while (0)
; #define PG8_WAIT_V(n) asm volatile("s_waitcnt vmcnt(" #n ")" ::: "memory")
; #define PG8_WAIT_L(n) asm volatile("s_waitcnt lgkmcnt(" #n ")" ::: "memory")
; #define PG8_BAR __builtin_amdgcn_s_barrier()
; #define PG8_SCHED __builtin_amdgcn_sched_barrier(0)
;     ...
;         for (int t = 0; t < nt; t += 2) {
;             const bool last = (t == nt - 2);
;             const char* a1 = cA + (size_t)(t + 1) * kstep;
;             const char* a2 = last ? nA : cA + (size_t)(t + 2) * kstep; const char* b2 = last ? nB : cB + (size_t)(t + 2) * kstep;
;             const char* a3 = a2 + kstep; const char* b3 = b2 + kstep;
;             if constexpr (SP2) {
;             PG8_LDB(B0, 0, 0); PG8_LDB(B1, 0, 1); PG8_SCHED; PG8_LDA(At, 0, 0); PG8_STAGE(PG8_SA(1, 1), a1 + hstepA, voffA);
;             PG8_WAIT_V(8); PG8_WAIT_L(0); PG8_BAR; PG8_MMA(0, 0, At, B0); PG8_MMA(0, 1, At, B1); PG8_BAR; PG8_SCHED;
;             PG8_LDA(At, 0, 1); PG8_STAGE(PG8_SB(0, 0), b2, voffB); PG8_STAGE(PG8_SB(0, 1), b2 + hstepB, voffB); PG8_STAGE(PG8_SA(0, 0), a2, voffA);
;             PG8_WAIT_V(8); PG8_WAIT_L(0); PG8_BAR; PG8_MMA(1, 0, At, B0); PG8_MMA(1, 1, At, B1); PG8_BAR; PG8_SCHED;
;             PG8_LDB(B0, 1, 0); PG8_LDB(B1, 1, 1); PG8_SCHED; PG8_LDA(At, 1, 0); PG8_STAGE(PG8_SA(0, 1), a2 + hstepA, voffA);
;             PG8_WAIT_V(8); PG8_WAIT_L(0); PG8_BAR; PG8_MMA(0, 0, At, B0); PG8_MMA(0, 1, At, B1); PG8_BAR; PG8_SCHED;
;             PG8_LDA(At, 1, 1); PG8_STAGE(PG8_SB(1, 0), b3, voffB); PG8_STAGE(PG8_SB(1, 1), b3 + hstepB, voffB); PG8_STAGE(PG8_SA(1, 0), a3, voffA);
;             PG8_WAIT_V(8); PG8_WAIT_L(0); PG8_BAR; PG8_MMA(1, 0, At, B0); PG8_MMA(1, 1, At, B1); PG8_BAR; PG8_SCHED;
.Ltl_up_2d:
	s_waitcnt lgkmcnt(0)
	s_barrier
	s_setprio 1
	s_waitcnt lgkmcnt(0)
	v_mfma_f32_16x16x32_bf16 v[46:49], v[130:133], v[162:165], v[46:49]
	v_mfma_f32_16x16x32_bf16 v[22:25], v[138:141], v[162:165], v[22:25]
	v_mfma_f32_16x16x32_bf16 v[42:45], v[130:133], v[170:173], v[42:45]
	v_mfma_f32_16x16x32_bf16 v[18:21], v[138:141], v[170:173], v[18:21]
	v_mfma_f32_16x16x32_bf16 v[38:41], v[130:133], v[190:193], v[38:41]
	v_mfma_f32_16x16x32_bf16 v[14:17], v[138:141], v[190:193], v[14:17]
	v_mfma_f32_16x16x32_bf16 v[78:81], v[130:133], v[198:201], v[78:81]
	v_mfma_f32_16x16x32_bf16 v[54:57], v[138:141], v[198:201], v[54:57]
	v_mfma_f32_16x16x32_bf16 v[46:49], v[134:137], v[166:169], v[46:49]
	v_mfma_f32_16x16x32_bf16 v[22:25], v[142:145], v[166:169], v[22:25]
	v_mfma_f32_16x16x32_bf16 v[42:45], v[134:137], v[174:177], v[42:45]
	v_mfma_f32_16x16x32_bf16 v[18:21], v[142:145], v[174:177], v[18:21]
	v_mfma_f32_16x16x32_bf16 v[38:41], v[134:137], v[194:197], v[38:41]
	v_mfma_f32_16x16x32_bf16 v[14:17], v[142:145], v[194:197], v[14:17]
	v_mfma_f32_16x16x32_bf16 v[78:81], v[134:137], v[202:205], v[78:81]
	v_mfma_f32_16x16x32_bf16 v[54:57], v[142:145], v[202:205], v[54:57]
	s_setprio 0
	s_setprio 1
	v_mfma_f32_16x16x32_bf16 v[34:37], v[146:149], v[162:165], v[34:37]
	v_mfma_f32_16x16x32_bf16 v[10:13], v[154:157], v[162:165], v[10:13]
	v_mfma_f32_16x16x32_bf16 v[30:33], v[146:149], v[170:173], v[30:33]
	v_mfma_f32_16x16x32_bf16 v[6:9], v[154:157], v[170:173], v[6:9]
	v_mfma_f32_16x16x32_bf16 v[26:29], v[146:149], v[190:193], v[26:29]
	v_mfma_f32_16x16x32_bf16 v[2:5], v[154:157], v[190:193], v[2:5]
	v_mfma_f32_16x16x32_bf16 v[74:77], v[146:149], v[198:201], v[74:77]
	v_mfma_f32_16x16x32_bf16 v[50:53], v[154:157], v[198:201], v[50:53]
	v_mfma_f32_16x16x32_bf16 v[34:37], v[150:153], v[166:169], v[34:37]
	v_mfma_f32_16x16x32_bf16 v[10:13], v[158:161], v[166:169], v[10:13]
	v_mfma_f32_16x16x32_bf16 v[30:33], v[150:153], v[174:177], v[30:33]
	v_mfma_f32_16x16x32_bf16 v[6:9], v[158:161], v[174:177], v[6:9]
	v_mfma_f32_16x16x32_bf16 v[26:29], v[150:153], v[194:197], v[26:29]
	v_mfma_f32_16x16x32_bf16 v[2:5], v[158:161], v[194:197], v[2:5]
	v_mfma_f32_16x16x32_bf16 v[74:77], v[150:153], v[202:205], v[74:77]
	v_mfma_f32_16x16x32_bf16 v[50:53], v[158:161], v[202:205], v[50:53]
	s_setprio 0
	s_waitcnt vmcnt(8)
	s_barrier
	s_add_i32 vcc_lo, vcc_lo, 2
	s_add_u32 s12, s12, 0x100
	s_addc_u32 s13, s13, 0
	s_add_u32 s37, s37, 0x100
	s_addc_u32 s41, s41, 0
	s_cmp_gt_u32 vcc_lo, 29
	s_cbranch_scc0 .LBB0_1783
	s_and_b64 vcc, exec, s[24:25]
	s_cbranch_vccz .LBB0_1786
	s_barrier
